# v075 plus priority 2 for the VALU-bound SwiGLU epilogue so the other half's MFMA segment does not throttle it
# baseline (speedup 1.0000x reference)
.LBB0_1568:
	s_setprio 2
	v_lshl_add_u32 v158, s16, 7, v161
	v_ashrrev_i32_e32 v158, 6, v158
	v_ashrrev_i32_e32 v159, 31, v158
	v_mov_b32_e32 v163, 0x58
	v_mad_i64_i32 v[158:159], s[14:15], s14, v163, v[158:159]
	v_exp_f32_e32 v163, v122
	v_pk_mul_f32 v[128:129], v[124:125], v[128:129]
	v_pk_mul_f32 v[120:121], v[116:117], v[120:121]
	v_pk_mul_f32 v[112:113], v[108:109], v[112:113]
	v_add_f32_e32 v163, 1.0, v163
	v_rcp_f32_e32 v166, v163
	v_exp_f32_e32 v163, v123
	v_pk_mul_f32 v[122:123], v[122:123], v[126:127]
	v_pk_mul_f32 v[104:105], v[100:101], v[104:105]
	v_pk_mul_f32 v[96:97], v[92:93], v[96:97]
	v_add_f32_e32 v163, 1.0, v163
	v_rcp_f32_e32 v167, v163
	v_pk_mul_f32 v[88:89], v[84:85], v[88:89]
	v_pk_mul_f32 v[80:81], v[76:77], v[80:81]
	v_pk_mul_f32 v[72:73], v[68:69], v[72:73]
	v_pk_mul_f32 v[122:123], v[166:167], v[122:123]
	v_pk_mul_f32 v[64:65], v[60:61], v[64:65]
	v_cvt_pk_bf16_f32 v122, v122, v123
	v_exp_f32_e32 v123, v124
	v_pk_mul_f32 v[56:57], v[52:53], v[56:57]
	v_pk_mul_f32 v[48:49], v[44:45], v[48:49]
	v_pk_mul_f32 v[40:41], v[36:37], v[40:41]
	v_add_f32_e32 v123, 1.0, v123
	v_rcp_f32_e32 v124, v123
	v_exp_f32_e32 v123, v125
	v_pk_mul_f32 v[32:33], v[28:29], v[32:33]
	v_pk_mul_f32 v[24:25], v[20:21], v[24:25]
	v_pk_mul_f32 v[16:17], v[12:13], v[16:17]
	v_add_f32_e32 v123, 1.0, v123
	v_rcp_f32_e32 v125, v123
	v_lshlrev_b64 v[158:159], 15, v[158:159]
	v_pk_mul_f32 v[8:9], v[4:5], v[8:9]
	v_lshl_add_u64 v[158:159], v[152:153], 0, v[158:159]
	v_pk_mul_f32 v[124:125], v[124:125], v[128:129]
	v_lshl_add_u64 v[164:165], v[158:159], 0, v[136:137]
	v_cvt_pk_bf16_f32 v123, v124, v125
	v_exp_f32_e32 v124, v114
	v_exp_f32_e32 v125, v115
	v_pk_mul_f32 v[114:115], v[114:115], v[118:119]
	s_mov_b64 s[14:15], -1
	v_add_f32_e32 v124, 1.0, v124
	v_add_f32_e32 v125, 1.0, v125
	v_rcp_f32_e32 v124, v124
	v_rcp_f32_e32 v125, v125
	s_andn2_b64 vcc, exec, s[34:35]
	v_pk_mul_f32 v[114:115], v[124:125], v[114:115]
	s_nop 0
	v_cvt_pk_bf16_f32 v124, v114, v115
	v_exp_f32_e32 v114, v116
	v_exp_f32_e32 v115, v117
	v_exp_f32_e32 v116, v106
	v_exp_f32_e32 v117, v107
	v_pk_mul_f32 v[106:107], v[106:107], v[110:111]
	v_add_f32_e32 v114, 1.0, v114
	v_add_f32_e32 v116, 1.0, v116
	v_add_f32_e32 v117, 1.0, v117
	v_rcp_f32_e32 v116, v116
	v_rcp_f32_e32 v117, v117
	v_add_f32_e32 v115, 1.0, v115
	v_rcp_f32_e32 v114, v114
	v_rcp_f32_e32 v115, v115
	v_pk_mul_f32 v[106:107], v[116:117], v[106:107]
	v_pk_mul_f32 v[114:115], v[114:115], v[120:121]
	v_cvt_pk_bf16_f32 v106, v106, v107
	v_exp_f32_e32 v107, v108
	v_cvt_pk_bf16_f32 v125, v114, v115
	v_lshl_add_u64 v[114:115], v[158:159], 0, v[138:139]
	global_store_dwordx4 v[164:165], v[122:125], off
	v_add_f32_e32 v107, 1.0, v107
	v_rcp_f32_e32 v108, v107
	v_exp_f32_e32 v107, v109
	s_nop 0
	v_add_f32_e32 v107, 1.0, v107
	v_rcp_f32_e32 v109, v107
	s_nop 0
	v_pk_mul_f32 v[108:109], v[108:109], v[112:113]
	s_nop 0
	v_cvt_pk_bf16_f32 v107, v108, v109
	v_exp_f32_e32 v108, v98
	v_exp_f32_e32 v109, v99
	v_pk_mul_f32 v[98:99], v[98:99], v[102:103]
	v_add_f32_e32 v108, 1.0, v108
	v_add_f32_e32 v109, 1.0, v109
	v_rcp_f32_e32 v108, v108
	v_rcp_f32_e32 v109, v109
	s_nop 0
	v_pk_mul_f32 v[98:99], v[108:109], v[98:99]
	s_nop 0
	v_cvt_pk_bf16_f32 v108, v98, v99
	v_exp_f32_e32 v98, v100
	v_exp_f32_e32 v99, v101
	v_exp_f32_e32 v100, v90
	v_exp_f32_e32 v101, v91
	v_pk_mul_f32 v[90:91], v[90:91], v[94:95]
	v_add_f32_e32 v98, 1.0, v98
	v_add_f32_e32 v100, 1.0, v100
	v_add_f32_e32 v101, 1.0, v101
	v_rcp_f32_e32 v100, v100
	v_rcp_f32_e32 v101, v101
	v_add_f32_e32 v99, 1.0, v99
	v_rcp_f32_e32 v98, v98
	v_rcp_f32_e32 v99, v99
	v_pk_mul_f32 v[90:91], v[100:101], v[90:91]
	v_pk_mul_f32 v[98:99], v[98:99], v[104:105]
	v_cvt_pk_bf16_f32 v90, v90, v91
	v_exp_f32_e32 v91, v92
	v_cvt_pk_bf16_f32 v109, v98, v99
	v_lshl_add_u64 v[98:99], v[158:159], 0, v[140:141]
	global_store_dwordx4 v[114:115], v[106:109], off
	v_add_f32_e32 v91, 1.0, v91
	v_rcp_f32_e32 v92, v91
	v_exp_f32_e32 v91, v93
	s_nop 0
	v_add_f32_e32 v91, 1.0, v91
	v_rcp_f32_e32 v93, v91
	s_nop 0
	v_pk_mul_f32 v[92:93], v[92:93], v[96:97]
	s_nop 0
	v_cvt_pk_bf16_f32 v91, v92, v93
	v_exp_f32_e32 v92, v82
	v_exp_f32_e32 v93, v83
	v_pk_mul_f32 v[82:83], v[82:83], v[86:87]
	v_add_f32_e32 v92, 1.0, v92
	v_add_f32_e32 v93, 1.0, v93
	v_rcp_f32_e32 v92, v92
	v_rcp_f32_e32 v93, v93
	s_nop 0
	v_pk_mul_f32 v[82:83], v[92:93], v[82:83]
	s_nop 0
	v_cvt_pk_bf16_f32 v92, v82, v83
	v_exp_f32_e32 v82, v84
	v_exp_f32_e32 v83, v85
	v_exp_f32_e32 v84, v74
	v_exp_f32_e32 v85, v75
	v_pk_mul_f32 v[74:75], v[74:75], v[78:79]
	v_add_f32_e32 v82, 1.0, v82
	v_add_f32_e32 v84, 1.0, v84
	v_add_f32_e32 v85, 1.0, v85
	v_rcp_f32_e32 v84, v84
	v_rcp_f32_e32 v85, v85
	v_add_f32_e32 v83, 1.0, v83
	v_rcp_f32_e32 v82, v82
	v_rcp_f32_e32 v83, v83
	v_pk_mul_f32 v[74:75], v[84:85], v[74:75]
	v_pk_mul_f32 v[82:83], v[82:83], v[88:89]
	v_cvt_pk_bf16_f32 v74, v74, v75
	v_exp_f32_e32 v75, v76
	v_cvt_pk_bf16_f32 v93, v82, v83
	v_lshl_add_u64 v[82:83], v[158:159], 0, v[142:143]
	global_store_dwordx4 v[98:99], v[90:93], off
	v_add_f32_e32 v75, 1.0, v75
	v_rcp_f32_e32 v76, v75
	v_exp_f32_e32 v75, v77
	s_nop 0
	v_add_f32_e32 v75, 1.0, v75
	v_rcp_f32_e32 v77, v75
	s_nop 0
	v_pk_mul_f32 v[76:77], v[76:77], v[80:81]
	s_nop 0
	v_cvt_pk_bf16_f32 v75, v76, v77
	v_exp_f32_e32 v76, v66
	v_exp_f32_e32 v77, v67
	v_pk_mul_f32 v[66:67], v[66:67], v[70:71]
	v_add_f32_e32 v76, 1.0, v76
	v_add_f32_e32 v77, 1.0, v77
	v_rcp_f32_e32 v76, v76
	v_rcp_f32_e32 v77, v77
	s_nop 0
	v_pk_mul_f32 v[66:67], v[76:77], v[66:67]
	s_nop 0
	v_cvt_pk_bf16_f32 v76, v66, v67
	v_exp_f32_e32 v66, v68
	v_exp_f32_e32 v67, v69
	v_exp_f32_e32 v68, v58
	v_exp_f32_e32 v69, v59
	v_pk_mul_f32 v[58:59], v[58:59], v[62:63]
	v_add_f32_e32 v66, 1.0, v66
	v_add_f32_e32 v68, 1.0, v68
	v_add_f32_e32 v69, 1.0, v69
	v_rcp_f32_e32 v68, v68
	v_rcp_f32_e32 v69, v69
	v_add_f32_e32 v67, 1.0, v67
	v_rcp_f32_e32 v66, v66
	v_rcp_f32_e32 v67, v67
	v_pk_mul_f32 v[58:59], v[68:69], v[58:59]
	v_pk_mul_f32 v[66:67], v[66:67], v[72:73]
	v_cvt_pk_bf16_f32 v58, v58, v59
	v_exp_f32_e32 v59, v60
	v_cvt_pk_bf16_f32 v77, v66, v67
	v_lshl_add_u64 v[66:67], v[158:159], 0, v[144:145]
	global_store_dwordx4 v[82:83], v[74:77], off
	v_add_f32_e32 v59, 1.0, v59
	v_rcp_f32_e32 v60, v59
	v_exp_f32_e32 v59, v61
	s_nop 0
	v_add_f32_e32 v59, 1.0, v59
	v_rcp_f32_e32 v61, v59
	s_nop 0
	v_pk_mul_f32 v[60:61], v[60:61], v[64:65]
	s_nop 0
	v_cvt_pk_bf16_f32 v59, v60, v61
	v_exp_f32_e32 v60, v50
	v_exp_f32_e32 v61, v51
	v_pk_mul_f32 v[50:51], v[50:51], v[54:55]
	v_add_f32_e32 v60, 1.0, v60
	v_add_f32_e32 v61, 1.0, v61
	v_rcp_f32_e32 v60, v60
	v_rcp_f32_e32 v61, v61
	s_nop 0
	v_pk_mul_f32 v[50:51], v[60:61], v[50:51]
	s_nop 0
	v_cvt_pk_bf16_f32 v60, v50, v51
	v_exp_f32_e32 v50, v52
	v_exp_f32_e32 v51, v53
	v_exp_f32_e32 v52, v42
	v_exp_f32_e32 v53, v43
	v_pk_mul_f32 v[42:43], v[42:43], v[46:47]
	v_add_f32_e32 v50, 1.0, v50
	v_add_f32_e32 v52, 1.0, v52
	v_add_f32_e32 v53, 1.0, v53
	v_rcp_f32_e32 v52, v52
	v_rcp_f32_e32 v53, v53
	v_add_f32_e32 v51, 1.0, v51
	v_rcp_f32_e32 v50, v50
	v_rcp_f32_e32 v51, v51
	v_pk_mul_f32 v[42:43], v[52:53], v[42:43]
	v_pk_mul_f32 v[50:51], v[50:51], v[56:57]
	v_cvt_pk_bf16_f32 v42, v42, v43
	v_exp_f32_e32 v43, v44
	v_cvt_pk_bf16_f32 v61, v50, v51
	v_lshl_add_u64 v[50:51], v[158:159], 0, v[146:147]
	global_store_dwordx4 v[66:67], v[58:61], off
	v_add_f32_e32 v43, 1.0, v43
	v_rcp_f32_e32 v44, v43
	v_exp_f32_e32 v43, v45
	s_nop 0
	v_add_f32_e32 v43, 1.0, v43
	v_rcp_f32_e32 v45, v43
	s_nop 0
	v_pk_mul_f32 v[44:45], v[44:45], v[48:49]
	s_nop 0
	v_cvt_pk_bf16_f32 v43, v44, v45
	v_exp_f32_e32 v44, v34
	v_exp_f32_e32 v45, v35
	v_pk_mul_f32 v[34:35], v[34:35], v[38:39]
	v_add_f32_e32 v44, 1.0, v44
	v_add_f32_e32 v45, 1.0, v45
	v_rcp_f32_e32 v44, v44
	v_rcp_f32_e32 v45, v45
	s_nop 0
	v_pk_mul_f32 v[34:35], v[44:45], v[34:35]
	s_nop 0
	v_cvt_pk_bf16_f32 v44, v34, v35
	v_exp_f32_e32 v34, v36
	v_exp_f32_e32 v35, v37
	v_exp_f32_e32 v36, v26
	v_exp_f32_e32 v37, v27
	v_pk_mul_f32 v[26:27], v[26:27], v[30:31]
	v_add_f32_e32 v34, 1.0, v34
	v_add_f32_e32 v36, 1.0, v36
	v_add_f32_e32 v37, 1.0, v37
	v_rcp_f32_e32 v36, v36
	v_rcp_f32_e32 v37, v37
	v_add_f32_e32 v35, 1.0, v35
	v_rcp_f32_e32 v34, v34
	v_rcp_f32_e32 v35, v35
	v_pk_mul_f32 v[26:27], v[36:37], v[26:27]
	v_pk_mul_f32 v[34:35], v[34:35], v[40:41]
	v_cvt_pk_bf16_f32 v26, v26, v27
	v_exp_f32_e32 v27, v28
	v_cvt_pk_bf16_f32 v45, v34, v35
	v_lshl_add_u64 v[34:35], v[158:159], 0, v[148:149]
	global_store_dwordx4 v[50:51], v[42:45], off
	v_add_f32_e32 v27, 1.0, v27
	v_rcp_f32_e32 v28, v27
	v_exp_f32_e32 v27, v29
	s_nop 0
	v_add_f32_e32 v27, 1.0, v27
	v_rcp_f32_e32 v29, v27
	s_nop 0
	v_pk_mul_f32 v[28:29], v[28:29], v[32:33]
	s_nop 0
	v_cvt_pk_bf16_f32 v27, v28, v29
	v_exp_f32_e32 v28, v18
	v_exp_f32_e32 v29, v19
	v_pk_mul_f32 v[18:19], v[18:19], v[22:23]
	v_add_f32_e32 v28, 1.0, v28
	v_add_f32_e32 v29, 1.0, v29
	v_rcp_f32_e32 v28, v28
	v_rcp_f32_e32 v29, v29
	s_nop 0
	v_pk_mul_f32 v[18:19], v[28:29], v[18:19]
	s_nop 0
	v_cvt_pk_bf16_f32 v28, v18, v19
	v_exp_f32_e32 v18, v20
	v_exp_f32_e32 v19, v21
	v_exp_f32_e32 v20, v10
	v_exp_f32_e32 v21, v11
	v_pk_mul_f32 v[10:11], v[10:11], v[14:15]
	v_add_f32_e32 v18, 1.0, v18
	v_add_f32_e32 v20, 1.0, v20
	v_add_f32_e32 v21, 1.0, v21
	v_rcp_f32_e32 v20, v20
	v_rcp_f32_e32 v21, v21
	v_add_f32_e32 v19, 1.0, v19
	v_rcp_f32_e32 v18, v18
	v_rcp_f32_e32 v19, v19
	v_pk_mul_f32 v[10:11], v[20:21], v[10:11]
	v_pk_mul_f32 v[18:19], v[18:19], v[24:25]
	v_cvt_pk_bf16_f32 v10, v10, v11
	v_exp_f32_e32 v11, v12
	v_cvt_pk_bf16_f32 v29, v18, v19
	v_lshl_add_u64 v[18:19], v[158:159], 0, v[150:151]
	global_store_dwordx4 v[34:35], v[26:29], off
	v_add_f32_e32 v11, 1.0, v11
	v_rcp_f32_e32 v12, v11
	v_exp_f32_e32 v11, v13
	s_nop 0
	v_add_f32_e32 v11, 1.0, v11
	v_rcp_f32_e32 v13, v11
	s_nop 0
	v_pk_mul_f32 v[12:13], v[12:13], v[16:17]
	s_nop 0
	v_cvt_pk_bf16_f32 v11, v12, v13
	v_exp_f32_e32 v12, v2
	v_exp_f32_e32 v13, v3
	v_pk_mul_f32 v[2:3], v[2:3], v[6:7]
	v_add_f32_e32 v12, 1.0, v12
	v_add_f32_e32 v13, 1.0, v13
	v_rcp_f32_e32 v12, v12
	v_rcp_f32_e32 v13, v13
	s_nop 0
	v_pk_mul_f32 v[2:3], v[12:13], v[2:3]
	s_nop 0
	v_cvt_pk_bf16_f32 v12, v2, v3
	v_exp_f32_e32 v2, v4
	v_exp_f32_e32 v3, v5
	v_add_f32_e32 v2, 1.0, v2
	v_add_f32_e32 v3, 1.0, v3
	v_rcp_f32_e32 v2, v2
	v_rcp_f32_e32 v3, v3
	s_nop 0
	v_pk_mul_f32 v[2:3], v[2:3], v[8:9]
	s_nop 0
	v_cvt_pk_bf16_f32 v13, v2, v3
	global_store_dwordx4 v[18:19], v[10:13], off
	s_setprio 0
	s_cbranch_vccnz .LBB0_1561
	s_andn2_b64 vcc, exec, s[0:1]
	s_cbranch_vccnz .LBB0_1560
	s_branch .LBB0_1560
